# P0 weight items: norm-scale loads issued ahead of the 32 strided weight loads instead of after them (one exposed latency less per item)
# baseline (speedup 1.0000x reference)
; DI void transpose_item(int kind, const float* g, const float* u, int ldn, int K, int Np, const float* kscale, bf16* WT, LAS float* scr, int item, int lane) {
;     ...
;     for (int i = 0; i < 32; ++i) scr[(2 * i + (lane >> 5)) * 33 + (lane & 31)] = v[i];
;     asm volatile("s_waitcnt lgkmcnt(0)" ::: "memory");
;     const int c = lane & 7;
;     float ks[8];
;     if (kscale) { const f32x4 a = *(const f32x4*)(kscale + k0 + 8 * c), b2 = *(const f32x4*)(kscale + k0 + 8 * c + 4); ks[0] = a.x; ks[1] = a.y; ks[2] = a.z; ks[3] = a.w; ks[4] = b2.x; ks[5] = b2.y; ks[6] = b2.z; ks[7] = b2.w; }
.LBB0_38:
	s_or_b64 exec, exec, s[72:73]
	v_add_u32_e32 v2, 0x400, v24
	s_waitcnt vmcnt(30)
	ds_write2_b32 v24, v11, v8 offset1:66
	s_waitcnt vmcnt(28)
	ds_write2_b32 v24, v7, v6 offset0:132 offset1:198
	s_waitcnt vmcnt(26)
	ds_write2_b32 v2, v5, v4 offset0:8 offset1:74
	s_waitcnt vmcnt(24)
	ds_write2_b32 v2, v1, v0 offset0:140 offset1:206
	v_add_u32_e32 v0, 0x800, v24
	s_waitcnt vmcnt(22)
	ds_write2_b32 v0, v32, v31 offset0:16 offset1:82
	s_waitcnt vmcnt(20)
	ds_write2_b32 v0, v30, v29 offset0:148 offset1:214
	v_add_u32_e32 v0, 0xc00, v24
	s_waitcnt vmcnt(18)
	ds_write2_b32 v0, v28, v27 offset0:24 offset1:90
	s_waitcnt vmcnt(16)
	ds_write2_b32 v0, v26, v13 offset0:156 offset1:222
	v_add_u32_e32 v0, 0x1000, v24
	s_waitcnt vmcnt(14)
	ds_write2_b32 v0, v40, v39 offset0:32 offset1:98
	s_waitcnt vmcnt(12)
	ds_write2_b32 v0, v38, v37 offset0:164 offset1:230
	v_add_u32_e32 v0, 0x1400, v24
	s_waitcnt vmcnt(10)
	ds_write2_b32 v0, v36, v35 offset0:40 offset1:106
	s_waitcnt vmcnt(8)
	ds_write2_b32 v0, v34, v33 offset0:172 offset1:238
	v_add_u32_e32 v0, 0x1800, v24
	s_waitcnt vmcnt(6)
	ds_write2_b32 v0, v48, v47 offset0:48 offset1:114
	s_waitcnt vmcnt(4)
	ds_write2_b32 v0, v46, v45 offset0:180 offset1:246
	v_add_u32_e32 v0, 0x1c00, v24
	s_waitcnt vmcnt(2)
	ds_write2_b32 v0, v44, v43 offset0:56 offset1:122
	s_waitcnt vmcnt(0)
	ds_write2_b32 v0, v42, v41 offset0:188 offset1:254
	s_waitcnt lgkmcnt(0)
	s_andn2_b64 vcc, exec, s[68:69]
	s_ashr_i32 s71, s70, 31
	s_cbranch_vccnz .LBB0_62
	v_mov_b32_e32 v0, v118
	v_mov_b32_e32 v1, v119
	v_mov_b32_e32 v2, v120
	v_mov_b32_e32 v3, v121
	v_mov_b32_e32 v4, v122
	v_mov_b32_e32 v5, v123
	v_mov_b32_e32 v6, v124
	v_mov_b32_e32 v7, v125

; DI void transpose_item(int kind, const float* g, const float* u, int ldn, int K, int Np, const float* kscale, bf16* WT, LAS float* scr, int item, int lane) {
;     ...
;     if (colp) {
;         const float* p = colp + (size_t)(k0 + (lane >> 5)) * ldn;
; #pragma unroll
;         for (int i = 0; i < 32; ++i) v[i] = p[(size_t)(2 * i) * ldn];
;     ...
;     if (kscale) { const f32x4 a = *(const f32x4*)(kscale + k0 + 8 * c), b2 = *(const f32x4*)(kscale + k0 + 8 * c + 4); ks[0] = a.x; ks[1] = a.y; ks[2] = a.z; ks[3] = a.w; ks[4] = b2.x; ks[5] = b2.y; ks[6] = b2.z; ks[7] = b2.w; }
.LBB0_60:
	s_lshl_b32 s70, s94, 6
	s_and_b64 vcc, exec, s[68:69]
	s_cbranch_vccz .Lp0_noks
	s_ashr_i32 s97, s70, 31
	s_mov_b32 s96, s70
	v_lshl_add_u64 v[116:117], s[96:97], 2, v[14:15]
	global_load_dwordx4 v[118:121], v[116:117], off
	global_load_dwordx4 v[122:125], v[116:117], off offset:16
.Lp0_noks:
	v_cmp_ne_u64_e32 vcc, 0, v[2:3]
	v_mov_b32_e32 v41, 0
	v_mov_b32_e32 v42, 0
	v_mov_b32_e32 v43, 0
	v_mov_b32_e32 v44, 0
	v_mov_b32_e32 v45, 0
	v_mov_b32_e32 v46, 0
	v_mov_b32_e32 v47, 0
	v_mov_b32_e32 v48, 0
	v_mov_b32_e32 v33, 0
	v_mov_b32_e32 v34, 0
	v_mov_b32_e32 v35, 0
	v_mov_b32_e32 v36, 0
	v_mov_b32_e32 v37, 0
	v_mov_b32_e32 v38, 0
	v_mov_b32_e32 v39, 0
	v_mov_b32_e32 v40, 0
	v_mov_b32_e32 v13, 0
	v_mov_b32_e32 v26, 0
	v_mov_b32_e32 v27, 0
	v_mov_b32_e32 v28, 0
	v_mov_b32_e32 v29, 0
	v_mov_b32_e32 v30, 0
	v_mov_b32_e32 v31, 0
	v_mov_b32_e32 v32, 0
	v_mov_b32_e32 v0, 0
	v_mov_b32_e32 v1, 0
	v_mov_b32_e32 v4, 0
	v_mov_b32_e32 v5, 0
	v_mov_b32_e32 v6, 0
	v_mov_b32_e32 v7, 0
	v_mov_b32_e32 v8, 0
	v_mov_b32_e32 v11, 0
	s_and_saveexec_b64 s[72:73], vcc
	s_cbranch_execz .LBB0_38
	v_or_b32_e32 v0, s70, v21
	s_ashr_i32 s71, s70, 31
	s_mul_i32 s71, s71, s78
	v_mad_u64_u32 v[0:1], s[94:95], v0, s78, 0
	v_add_u32_e32 v1, s71, v1
	v_lshl_add_u64 v[2:3], v[0:1], 2, v[2:3]
	v_lshl_add_u64 v[0:1], s[0:1], 2, v[2:3]
	v_lshl_add_u64 v[4:5], s[6:7], 2, v[2:3]
	v_lshl_add_u64 v[26:27], s[8:9], 2, v[2:3]
	v_lshl_add_u64 v[28:29], s[10:11], 2, v[2:3]
	v_lshl_add_u64 v[34:35], s[16:17], 2, v[2:3]
	v_lshl_add_u64 v[30:31], s[12:13], 2, v[2:3]
	v_lshl_add_u64 v[32:33], s[14:15], 2, v[2:3]
	global_load_dword v11, v[2:3], off
	global_load_dword v8, v[0:1], off
	global_load_dword v7, v[4:5], off
	global_load_dword v6, v[26:27], off
	s_nop 0
	global_load_dword v5, v[28:29], off
	global_load_dword v4, v[30:31], off
	global_load_dword v1, v[32:33], off
	global_load_dword v0, v[34:35], off
	v_lshl_add_u64 v[26:27], s[18:19], 2, v[2:3]
	v_lshl_add_u64 v[28:29], s[20:21], 2, v[2:3]
	v_lshl_add_u64 v[34:35], s[22:23], 2, v[2:3]
	v_lshl_add_u64 v[36:37], s[24:25], 2, v[2:3]
	v_lshl_add_u64 v[42:43], s[30:31], 2, v[2:3]
	v_lshl_add_u64 v[44:45], s[34:35], 2, v[2:3]
	v_lshl_add_u64 v[38:39], s[26:27], 2, v[2:3]
	v_lshl_add_u64 v[40:41], s[28:29], 2, v[2:3]
	global_load_dword v32, v[26:27], off
	global_load_dword v31, v[28:29], off
	global_load_dword v30, v[34:35], off
	s_nop 0
	global_load_dword v29, v[36:37], off
	global_load_dword v28, v[38:39], off
	global_load_dword v27, v[40:41], off
	global_load_dword v26, v[42:43], off
	global_load_dword v13, v[44:45], off
	v_lshl_add_u64 v[34:35], s[36:37], 2, v[2:3]
	v_lshl_add_u64 v[36:37], s[38:39], 2, v[2:3]
	v_lshl_add_u64 v[42:43], s[40:41], 2, v[2:3]
	v_lshl_add_u64 v[44:45], s[42:43], 2, v[2:3]
	v_lshl_add_u64 v[46:47], s[44:45], 2, v[2:3]
	v_lshl_add_u64 v[48:49], s[46:47], 2, v[2:3]
	v_lshl_add_u64 v[50:51], s[48:49], 2, v[2:3]
	v_lshl_add_u64 v[52:53], s[50:51], 2, v[2:3]
	global_load_dword v40, v[34:35], off
	global_load_dword v39, v[36:37], off
	global_load_dword v38, v[42:43], off
	s_nop 0
	global_load_dword v37, v[44:45], off
	global_load_dword v36, v[46:47], off
	global_load_dword v35, v[48:49], off
	global_load_dword v34, v[50:51], off
	global_load_dword v33, v[52:53], off
	v_lshl_add_u64 v[42:43], s[52:53], 2, v[2:3]
	v_lshl_add_u64 v[44:45], s[54:55], 2, v[2:3]
	v_lshl_add_u64 v[50:51], s[56:57], 2, v[2:3]
	v_lshl_add_u64 v[52:53], s[58:59], 2, v[2:3]
	v_lshl_add_u64 v[54:55], s[60:61], 2, v[2:3]
	v_lshl_add_u64 v[56:57], s[62:63], 2, v[2:3]
	v_lshl_add_u64 v[58:59], s[64:65], 2, v[2:3]
	v_lshl_add_u64 v[2:3], s[66:67], 2, v[2:3]
	global_load_dword v48, v[42:43], off
	global_load_dword v47, v[44:45], off
	global_load_dword v46, v[50:51], off
	s_nop 0
	global_load_dword v45, v[52:53], off
	global_load_dword v44, v[54:55], off
	global_load_dword v43, v[56:57], off
	global_load_dword v42, v[58:59], off
	global_load_dword v41, v[2:3], off
	s_branch .LBB0_38
